# RWKV producer: second-half post-processing (group norm + bonus) batched over the 8 tokens of a tile with stage-interleaved DPP reductions; partial/bonus load addresses generated by stride
# speedup vs baseline: 1.0569x; 1.0249x over previous
.LBB0_407:
	s_add_i32 s30, s88, -3
	s_cmp_lg_u32 s90, 0
	s_cselect_b64 s[16:17], -1, 0
	s_cmp_eq_u32 s90, 0
	s_cselect_b64 s[0:1], -1, 0
	s_cmp_gt_u32 s25, s29
	s_cselect_b64 s[96:97], -1, 0
	s_cmp_le_u32 s25, s29
	s_cselect_b64 s[2:3], -1, 0
	s_or_b64 s[0:1], s[0:1], s[2:3]
	s_and_b64 vcc, exec, s[0:1]
	s_cbranch_vccnz .LBB0_437
	s_lshl_b64 s[0:1], s[30:31], 3
	s_add_u32 s0, s0, s92
	s_addc_u32 s1, s1, s93
	s_add_u32 s2, s23, s90
	s_addc_u32 s3, s24, s91
	s_add_u32 s2, s2, 7
	s_addc_u32 s3, s3, 0
	v_mov_b32_e32 v32, s0
	v_mov_b32_e32 v33, s1
	v_mov_b32_e32 v34, s2
	v_mov_b32_e32 v35, s3
	v_cndmask_b32_e64 v32, v32, v34, s[6:7]
	v_cndmask_b32_e64 v33, v33, v35, s[6:7]
	v_lshlrev_b64 v[34:35], 13, v[32:33]
	v_lshlrev_b64 v[36:37], 8, v[32:33]
	v_lshl_add_u64 v[226:227], v[118:119], 0, v[34:35]
	v_lshl_add_u64 v[36:37], v[120:121], 0, v[36:37]
	v_mov_b32_e32 v38, 0x2000
	v_mov_b32_e32 v39, 0xffffe000
	v_cndmask_b32_e64 v228, v38, v39, s[6:7]
	v_cndmask_b32_e64 v229, 0, -1, s[6:7]
	v_mov_b32_e32 v38, 0x100
	v_mov_b32_e32 v39, 0xffffff00
	v_cndmask_b32_e64 v40, v38, v39, s[6:7]
	v_mov_b32_e32 v41, v229
	v_mov_b32_e32 v34, v226
	v_mov_b32_e32 v35, v227
	global_load_ushort v204, v[34:35], off
	global_load_dword v212, v[36:37], off
	v_lshl_add_u64 v[34:35], v[34:35], 0, v[228:229]
	v_lshl_add_u64 v[36:37], v[36:37], 0, v[40:41]
	global_load_ushort v205, v[34:35], off
	global_load_dword v213, v[36:37], off
	v_lshl_add_u64 v[34:35], v[34:35], 0, v[228:229]
	v_lshl_add_u64 v[36:37], v[36:37], 0, v[40:41]
	global_load_ushort v206, v[34:35], off
	global_load_dword v214, v[36:37], off
	v_lshl_add_u64 v[34:35], v[34:35], 0, v[228:229]
	v_lshl_add_u64 v[36:37], v[36:37], 0, v[40:41]
	global_load_ushort v207, v[34:35], off
	global_load_dword v215, v[36:37], off
	v_lshl_add_u64 v[34:35], v[34:35], 0, v[228:229]
	v_lshl_add_u64 v[36:37], v[36:37], 0, v[40:41]
	global_load_ushort v208, v[34:35], off
	global_load_dword v216, v[36:37], off
	v_lshl_add_u64 v[34:35], v[34:35], 0, v[228:229]
	v_lshl_add_u64 v[36:37], v[36:37], 0, v[40:41]
	global_load_ushort v209, v[34:35], off
	global_load_dword v217, v[36:37], off
	v_lshl_add_u64 v[34:35], v[34:35], 0, v[228:229]
	v_lshl_add_u64 v[36:37], v[36:37], 0, v[40:41]
	global_load_ushort v210, v[34:35], off
	global_load_dword v218, v[36:37], off
	v_lshl_add_u64 v[34:35], v[34:35], 0, v[228:229]
	v_lshl_add_u64 v[36:37], v[36:37], 0, v[40:41]
	global_load_ushort v211, v[34:35], off
	global_load_dword v219, v[36:37], off

.LBB0_439:
	s_andn2_b64 vcc, exec, s[16:17]
	s_cbranch_vccnz .LBB0_510
	s_and_b64 vcc, exec, s[96:97]
	s_cbranch_vccnz .Lp2_post
	s_add_i32 s2, s22, -4
	v_and_or_b32 v220, s2, 2, v171
	s_lshl_b64 s[2:3], s[30:31], 3
	s_add_u32 s30, s2, s92
	s_addc_u32 s68, s3, s93
	s_add_u32 s26, s23, s90
	s_addc_u32 s27, s24, s91
	s_add_u32 s2, s26, 7
	s_addc_u32 s3, s27, 0
	v_mov_b32_e32 v64, s3
	v_mov_b32_e32 v128, s68
	v_cndmask_b32_e64 v129, v64, v128, s[4:5]
	v_mov_b32_e32 v64, s2
	v_mov_b32_e32 v128, s30
	v_cndmask_b32_e64 v128, v64, v128, s[4:5]
	v_lshl_or_b32 v64, v220, 11, v173
	v_lshlrev_b32_e32 v219, 5, v220
	ds_read_b32 v222, v64 offset:49152
	ds_read_b32 v221, v219 offset:57344
	v_lshlrev_b64 v[130:131], 13, v[128:129]
	s_mov_b64 s[16:17], -1
	s_and_b64 vcc, exec, s[96:97]
	v_lshl_add_u64 v[130:131], v[118:119], 0, v[130:131]
	s_cbranch_vccz .LBB0_444
	s_waitcnt vmcnt(15)
	v_lshlrev_b32_e32 v223, 16, v204
	s_waitcnt lgkmcnt(1)
	v_add_f32_e32 v223, v222, v223
	v_mul_u32_u24_e32 v64, 0x3000, v220
	v_or_b32_e32 v64, v173, v64
	v_add_f32_dpp v224, v223, v223 quad_perm:[1,0,3,2] row_mask:0xf bank_mask:0xf bound_ctrl:1
	ds_read_b32 v64, v64 offset:1280
	s_nop 0
	v_add_f32_dpp v224, v224, v224 quad_perm:[2,3,0,1] row_mask:0xf bank_mask:0xf bound_ctrl:1
	s_nop 1
	v_add_f32_dpp v224, v224, v224 row_ror:4 row_mask:0xf bank_mask:0xf bound_ctrl:1
	s_nop 1
	v_add_f32_dpp v224, v224, v224 row_ror:8 row_mask:0xf bank_mask:0xf bound_ctrl:1
	s_nop 0
	v_readlane_b32 s16, v224, 16
	v_readlane_b32 s17, v224, 48
	v_readlane_b32 s2, v224, 0
	v_readlane_b32 s3, v224, 32
	v_mov_b32_e32 v224, s16
	v_mov_b32_e32 v225, s17
	v_pk_add_f32 v[224:225], s[2:3], v[224:225]
	s_nop 0
	v_add_f32_e32 v224, v224, v225
	v_fmac_f32_e32 v223, 0xbc800000, v224
	v_mul_f32_e32 v224, v223, v223
	s_nop 1
	v_mov_b32_dpp v224, v224 quad_perm:[1,0,3,2] row_mask:0xf bank_mask:0xf bound_ctrl:1
	v_fmac_f32_e32 v224, v223, v223
	s_nop 1
	v_add_f32_dpp v224, v224, v224 quad_perm:[2,3,0,1] row_mask:0xf bank_mask:0xf bound_ctrl:1
	s_nop 1
	v_add_f32_dpp v224, v224, v224 row_ror:4 row_mask:0xf bank_mask:0xf bound_ctrl:1
	s_nop 1
	v_add_f32_dpp v224, v224, v224 row_ror:8 row_mask:0xf bank_mask:0xf bound_ctrl:1
	s_nop 0
	v_readlane_b32 s16, v224, 16
	v_readlane_b32 s17, v224, 48
	v_readlane_b32 s2, v224, 0
	v_readlane_b32 s3, v224, 32
	v_mov_b32_e32 v224, s16
	v_mov_b32_e32 v225, s17
	v_pk_add_f32 v[224:225], s[2:3], v[224:225]
	s_nop 0
	v_add_f32_e32 v224, v224, v225
	v_fmamk_f32 v224, v224, 0x3c800000, v190
	v_rsq_f32_e32 v225, v224
	s_waitcnt vmcnt(14) lgkmcnt(1)
	v_add_f32_e32 v224, v152, v221
	v_mul_f32_e32 v225, v223, v225
	s_waitcnt lgkmcnt(0)
	v_pk_mul_f32 v[224:225], v[224:225], v[64:65]
	s_nop 0
	v_add_f32_e32 v64, v141, v225
	v_add_f32_e32 v64, v224, v64
	v_bfe_u32 v223, v64, 16, 1
	v_add3_u32 v64, v64, v223, s82
	global_store_short_d16_hi v[130:131], v64, off
	s_cbranch_execz .LBB0_445

.Lp2_post:
	s_add_i32 s2, s22, -4
	v_and_or_b32 v220, s2, 2, v171
	v_lshl_or_b32 v221, v220, 11, v173
	v_mul_u32_u24_e32 v222, 0x3000, v220
	v_lshlrev_b32_e32 v223, 5, v220
	v_or_b32_e32 v222, v173, v222
	ds_read_b32 v230, v221 offset:49152
	ds_read_b32 v231, v221 offset:49408
	ds_read_b32 v232, v221 offset:49664
	ds_read_b32 v233, v221 offset:49920
	ds_read_b32 v234, v221 offset:50176
	ds_read_b32 v235, v221 offset:50432
	ds_read_b32 v236, v221 offset:50688
	ds_read_b32 v237, v221 offset:50944
	ds_read_b32 v238, v222 offset:1280
	ds_read_b32 v239, v222 offset:2816
	ds_read_b32 v240, v222 offset:4352
	ds_read_b32 v241, v222 offset:5888
	ds_read_b32 v242, v222 offset:7424
	ds_read_b32 v243, v222 offset:8960
	ds_read_b32 v244, v222 offset:10496
	ds_read_b32 v245, v222 offset:12032
	ds_read_b32 v64, v223 offset:57344
	ds_read_b32 v128, v223 offset:57348
	ds_read_b32 v129, v223 offset:57352
	ds_read_b32 v130, v223 offset:57356
	ds_read_b32 v131, v223 offset:57360
	ds_read_b32 v246, v223 offset:57364
	ds_read_b32 v247, v223 offset:57368
	ds_read_b32 v225, v223 offset:57372
	s_and_b64 vcc, exec, s[0:1]
	s_cbranch_vccz .Lp2_w0
	s_waitcnt vmcnt(18)
	s_branch .Lp2_w1

.Lp2_w1:
	s_waitcnt lgkmcnt(0)
	v_lshlrev_b32_e32 v204, 16, v204
	v_lshlrev_b32_e32 v205, 16, v205
	v_lshlrev_b32_e32 v206, 16, v206
	v_lshlrev_b32_e32 v207, 16, v207
	v_lshlrev_b32_e32 v208, 16, v208
	v_lshlrev_b32_e32 v209, 16, v209
	v_lshlrev_b32_e32 v210, 16, v210
	v_lshlrev_b32_e32 v211, 16, v211
	v_add_f32_e32 v230, v230, v204
	v_add_f32_e32 v231, v231, v205
	v_add_f32_e32 v232, v232, v206
	v_add_f32_e32 v233, v233, v207
	v_add_f32_e32 v234, v234, v208
	v_add_f32_e32 v235, v235, v209
	v_add_f32_e32 v236, v236, v210
	v_add_f32_e32 v237, v237, v211
	v_add_f32_e32 v212, v212, v64
	v_add_f32_e32 v213, v213, v128
	v_add_f32_e32 v214, v214, v129
	v_add_f32_e32 v215, v215, v130
	v_add_f32_e32 v216, v216, v131
	v_add_f32_e32 v217, v217, v246
	v_add_f32_e32 v218, v218, v247
	v_add_f32_e32 v219, v219, v225
	v_add_f32_dpp v204, v230, v230 quad_perm:[1,0,3,2] row_mask:0xf bank_mask:0xf bound_ctrl:1
	v_add_f32_dpp v205, v231, v231 quad_perm:[1,0,3,2] row_mask:0xf bank_mask:0xf bound_ctrl:1
	v_add_f32_dpp v206, v232, v232 quad_perm:[1,0,3,2] row_mask:0xf bank_mask:0xf bound_ctrl:1
	v_add_f32_dpp v207, v233, v233 quad_perm:[1,0,3,2] row_mask:0xf bank_mask:0xf bound_ctrl:1
	v_add_f32_dpp v208, v234, v234 quad_perm:[1,0,3,2] row_mask:0xf bank_mask:0xf bound_ctrl:1
	v_add_f32_dpp v209, v235, v235 quad_perm:[1,0,3,2] row_mask:0xf bank_mask:0xf bound_ctrl:1
	v_add_f32_dpp v210, v236, v236 quad_perm:[1,0,3,2] row_mask:0xf bank_mask:0xf bound_ctrl:1
	v_add_f32_dpp v211, v237, v237 quad_perm:[1,0,3,2] row_mask:0xf bank_mask:0xf bound_ctrl:1
	v_add_f32_dpp v204, v204, v204 quad_perm:[2,3,0,1] row_mask:0xf bank_mask:0xf bound_ctrl:1
	v_add_f32_dpp v205, v205, v205 quad_perm:[2,3,0,1] row_mask:0xf bank_mask:0xf bound_ctrl:1
	v_add_f32_dpp v206, v206, v206 quad_perm:[2,3,0,1] row_mask:0xf bank_mask:0xf bound_ctrl:1
	v_add_f32_dpp v207, v207, v207 quad_perm:[2,3,0,1] row_mask:0xf bank_mask:0xf bound_ctrl:1
	v_add_f32_dpp v208, v208, v208 quad_perm:[2,3,0,1] row_mask:0xf bank_mask:0xf bound_ctrl:1
	v_add_f32_dpp v209, v209, v209 quad_perm:[2,3,0,1] row_mask:0xf bank_mask:0xf bound_ctrl:1
	v_add_f32_dpp v210, v210, v210 quad_perm:[2,3,0,1] row_mask:0xf bank_mask:0xf bound_ctrl:1
	v_add_f32_dpp v211, v211, v211 quad_perm:[2,3,0,1] row_mask:0xf bank_mask:0xf bound_ctrl:1
	v_add_f32_dpp v204, v204, v204 row_ror:4 row_mask:0xf bank_mask:0xf bound_ctrl:1
	v_add_f32_dpp v205, v205, v205 row_ror:4 row_mask:0xf bank_mask:0xf bound_ctrl:1
	v_add_f32_dpp v206, v206, v206 row_ror:4 row_mask:0xf bank_mask:0xf bound_ctrl:1
	v_add_f32_dpp v207, v207, v207 row_ror:4 row_mask:0xf bank_mask:0xf bound_ctrl:1
	v_add_f32_dpp v208, v208, v208 row_ror:4 row_mask:0xf bank_mask:0xf bound_ctrl:1
	v_add_f32_dpp v209, v209, v209 row_ror:4 row_mask:0xf bank_mask:0xf bound_ctrl:1
	v_add_f32_dpp v210, v210, v210 row_ror:4 row_mask:0xf bank_mask:0xf bound_ctrl:1
	v_add_f32_dpp v211, v211, v211 row_ror:4 row_mask:0xf bank_mask:0xf bound_ctrl:1
	v_add_f32_dpp v204, v204, v204 row_ror:8 row_mask:0xf bank_mask:0xf bound_ctrl:1
	v_add_f32_dpp v205, v205, v205 row_ror:8 row_mask:0xf bank_mask:0xf bound_ctrl:1
	v_add_f32_dpp v206, v206, v206 row_ror:8 row_mask:0xf bank_mask:0xf bound_ctrl:1
	v_add_f32_dpp v207, v207, v207 row_ror:8 row_mask:0xf bank_mask:0xf bound_ctrl:1
	v_add_f32_dpp v208, v208, v208 row_ror:8 row_mask:0xf bank_mask:0xf bound_ctrl:1
	v_add_f32_dpp v209, v209, v209 row_ror:8 row_mask:0xf bank_mask:0xf bound_ctrl:1
	v_add_f32_dpp v210, v210, v210 row_ror:8 row_mask:0xf bank_mask:0xf bound_ctrl:1
	v_add_f32_dpp v211, v211, v211 row_ror:8 row_mask:0xf bank_mask:0xf bound_ctrl:1
	v_readlane_b32 s16, v204, 16
	v_readlane_b32 s17, v204, 48
	v_readlane_b32 s2, v204, 0
	v_readlane_b32 s3, v204, 32
	v_readlane_b32 s20, v205, 16
	v_readlane_b32 s21, v205, 48
	v_readlane_b32 s26, v205, 0
	v_readlane_b32 s27, v205, 32
	v_mov_b32_e32 v204, s2
	v_add_f32_e32 v204, s16, v204
	v_add_f32_e32 v204, s3, v204
	v_add_f32_e32 v204, s17, v204
	v_mov_b32_e32 v205, s26
	v_add_f32_e32 v205, s20, v205
	v_add_f32_e32 v205, s27, v205
	v_add_f32_e32 v205, s21, v205
	v_readlane_b32 s16, v206, 16
	v_readlane_b32 s17, v206, 48
	v_readlane_b32 s2, v206, 0
	v_readlane_b32 s3, v206, 32
	v_readlane_b32 s20, v207, 16
	v_readlane_b32 s21, v207, 48
	v_readlane_b32 s26, v207, 0
	v_readlane_b32 s27, v207, 32
	v_mov_b32_e32 v206, s2
	v_add_f32_e32 v206, s16, v206
	v_add_f32_e32 v206, s3, v206
	v_add_f32_e32 v206, s17, v206
	v_mov_b32_e32 v207, s26
	v_add_f32_e32 v207, s20, v207
	v_add_f32_e32 v207, s27, v207
	v_add_f32_e32 v207, s21, v207
	v_readlane_b32 s16, v208, 16
	v_readlane_b32 s17, v208, 48
	v_readlane_b32 s2, v208, 0
	v_readlane_b32 s3, v208, 32
	v_readlane_b32 s20, v209, 16
	v_readlane_b32 s21, v209, 48
	v_readlane_b32 s26, v209, 0
	v_readlane_b32 s27, v209, 32
	v_mov_b32_e32 v208, s2
	v_add_f32_e32 v208, s16, v208
	v_add_f32_e32 v208, s3, v208
	v_add_f32_e32 v208, s17, v208
	v_mov_b32_e32 v209, s26
	v_add_f32_e32 v209, s20, v209
	v_add_f32_e32 v209, s27, v209
	v_add_f32_e32 v209, s21, v209
	v_readlane_b32 s16, v210, 16
	v_readlane_b32 s17, v210, 48
	v_readlane_b32 s2, v210, 0
	v_readlane_b32 s3, v210, 32
	v_readlane_b32 s20, v211, 16
	v_readlane_b32 s21, v211, 48
	v_readlane_b32 s26, v211, 0
	v_readlane_b32 s27, v211, 32
	v_mov_b32_e32 v210, s2
	v_add_f32_e32 v210, s16, v210
	v_add_f32_e32 v210, s3, v210
	v_add_f32_e32 v210, s17, v210
	v_mov_b32_e32 v211, s26
	v_add_f32_e32 v211, s20, v211
	v_add_f32_e32 v211, s27, v211
	v_add_f32_e32 v211, s21, v211
	v_fmac_f32_e32 v230, 0xbc800000, v204
	v_fmac_f32_e32 v231, 0xbc800000, v205
	v_fmac_f32_e32 v232, 0xbc800000, v206
	v_fmac_f32_e32 v233, 0xbc800000, v207
	v_fmac_f32_e32 v234, 0xbc800000, v208
	v_fmac_f32_e32 v235, 0xbc800000, v209
	v_fmac_f32_e32 v236, 0xbc800000, v210
	v_fmac_f32_e32 v237, 0xbc800000, v211
	v_mul_f32_e32 v204, v230, v230
	v_mul_f32_e32 v205, v231, v231
	v_mul_f32_e32 v206, v232, v232
	v_mul_f32_e32 v207, v233, v233
	v_mul_f32_e32 v208, v234, v234
	v_mul_f32_e32 v209, v235, v235
	v_mul_f32_e32 v210, v236, v236
	v_mul_f32_e32 v211, v237, v237
	v_add_f32_dpp v204, v204, v204 quad_perm:[1,0,3,2] row_mask:0xf bank_mask:0xf bound_ctrl:1
	v_add_f32_dpp v205, v205, v205 quad_perm:[1,0,3,2] row_mask:0xf bank_mask:0xf bound_ctrl:1
	v_add_f32_dpp v206, v206, v206 quad_perm:[1,0,3,2] row_mask:0xf bank_mask:0xf bound_ctrl:1
	v_add_f32_dpp v207, v207, v207 quad_perm:[1,0,3,2] row_mask:0xf bank_mask:0xf bound_ctrl:1
	v_add_f32_dpp v208, v208, v208 quad_perm:[1,0,3,2] row_mask:0xf bank_mask:0xf bound_ctrl:1
	v_add_f32_dpp v209, v209, v209 quad_perm:[1,0,3,2] row_mask:0xf bank_mask:0xf bound_ctrl:1
	v_add_f32_dpp v210, v210, v210 quad_perm:[1,0,3,2] row_mask:0xf bank_mask:0xf bound_ctrl:1
	v_add_f32_dpp v211, v211, v211 quad_perm:[1,0,3,2] row_mask:0xf bank_mask:0xf bound_ctrl:1
	v_add_f32_dpp v204, v204, v204 quad_perm:[2,3,0,1] row_mask:0xf bank_mask:0xf bound_ctrl:1
	v_add_f32_dpp v205, v205, v205 quad_perm:[2,3,0,1] row_mask:0xf bank_mask:0xf bound_ctrl:1
	v_add_f32_dpp v206, v206, v206 quad_perm:[2,3,0,1] row_mask:0xf bank_mask:0xf bound_ctrl:1
	v_add_f32_dpp v207, v207, v207 quad_perm:[2,3,0,1] row_mask:0xf bank_mask:0xf bound_ctrl:1
	v_add_f32_dpp v208, v208, v208 quad_perm:[2,3,0,1] row_mask:0xf bank_mask:0xf bound_ctrl:1
	v_add_f32_dpp v209, v209, v209 quad_perm:[2,3,0,1] row_mask:0xf bank_mask:0xf bound_ctrl:1
	v_add_f32_dpp v210, v210, v210 quad_perm:[2,3,0,1] row_mask:0xf bank_mask:0xf bound_ctrl:1
	v_add_f32_dpp v211, v211, v211 quad_perm:[2,3,0,1] row_mask:0xf bank_mask:0xf bound_ctrl:1
	v_add_f32_dpp v204, v204, v204 row_ror:4 row_mask:0xf bank_mask:0xf bound_ctrl:1
	v_add_f32_dpp v205, v205, v205 row_ror:4 row_mask:0xf bank_mask:0xf bound_ctrl:1
	v_add_f32_dpp v206, v206, v206 row_ror:4 row_mask:0xf bank_mask:0xf bound_ctrl:1
	v_add_f32_dpp v207, v207, v207 row_ror:4 row_mask:0xf bank_mask:0xf bound_ctrl:1
	v_add_f32_dpp v208, v208, v208 row_ror:4 row_mask:0xf bank_mask:0xf bound_ctrl:1
	v_add_f32_dpp v209, v209, v209 row_ror:4 row_mask:0xf bank_mask:0xf bound_ctrl:1
	v_add_f32_dpp v210, v210, v210 row_ror:4 row_mask:0xf bank_mask:0xf bound_ctrl:1
	v_add_f32_dpp v211, v211, v211 row_ror:4 row_mask:0xf bank_mask:0xf bound_ctrl:1
	v_add_f32_dpp v204, v204, v204 row_ror:8 row_mask:0xf bank_mask:0xf bound_ctrl:1
	v_add_f32_dpp v205, v205, v205 row_ror:8 row_mask:0xf bank_mask:0xf bound_ctrl:1
	v_add_f32_dpp v206, v206, v206 row_ror:8 row_mask:0xf bank_mask:0xf bound_ctrl:1
	v_add_f32_dpp v207, v207, v207 row_ror:8 row_mask:0xf bank_mask:0xf bound_ctrl:1
	v_add_f32_dpp v208, v208, v208 row_ror:8 row_mask:0xf bank_mask:0xf bound_ctrl:1
	v_add_f32_dpp v209, v209, v209 row_ror:8 row_mask:0xf bank_mask:0xf bound_ctrl:1
	v_add_f32_dpp v210, v210, v210 row_ror:8 row_mask:0xf bank_mask:0xf bound_ctrl:1
	v_add_f32_dpp v211, v211, v211 row_ror:8 row_mask:0xf bank_mask:0xf bound_ctrl:1
	v_readlane_b32 s16, v204, 16
	v_readlane_b32 s17, v204, 48
	v_readlane_b32 s2, v204, 0
	v_readlane_b32 s3, v204, 32
	v_readlane_b32 s20, v205, 16
	v_readlane_b32 s21, v205, 48
	v_readlane_b32 s26, v205, 0
	v_readlane_b32 s27, v205, 32
	v_mov_b32_e32 v204, s2
	v_add_f32_e32 v204, s16, v204
	v_add_f32_e32 v204, s3, v204
	v_add_f32_e32 v204, s17, v204
	v_mov_b32_e32 v205, s26
	v_add_f32_e32 v205, s20, v205
	v_add_f32_e32 v205, s27, v205
	v_add_f32_e32 v205, s21, v205
	v_readlane_b32 s16, v206, 16
	v_readlane_b32 s17, v206, 48
	v_readlane_b32 s2, v206, 0
	v_readlane_b32 s3, v206, 32
	v_readlane_b32 s20, v207, 16
	v_readlane_b32 s21, v207, 48
	v_readlane_b32 s26, v207, 0
	v_readlane_b32 s27, v207, 32
	v_mov_b32_e32 v206, s2
	v_add_f32_e32 v206, s16, v206
	v_add_f32_e32 v206, s3, v206
	v_add_f32_e32 v206, s17, v206
	v_mov_b32_e32 v207, s26
	v_add_f32_e32 v207, s20, v207
	v_add_f32_e32 v207, s27, v207
	v_add_f32_e32 v207, s21, v207
	v_readlane_b32 s16, v208, 16
	v_readlane_b32 s17, v208, 48
	v_readlane_b32 s2, v208, 0
	v_readlane_b32 s3, v208, 32
	v_readlane_b32 s20, v209, 16
	v_readlane_b32 s21, v209, 48
	v_readlane_b32 s26, v209, 0
	v_readlane_b32 s27, v209, 32
	v_mov_b32_e32 v208, s2
	v_add_f32_e32 v208, s16, v208
	v_add_f32_e32 v208, s3, v208
	v_add_f32_e32 v208, s17, v208
	v_mov_b32_e32 v209, s26
	v_add_f32_e32 v209, s20, v209
	v_add_f32_e32 v209, s27, v209
	v_add_f32_e32 v209, s21, v209
	v_readlane_b32 s16, v210, 16
	v_readlane_b32 s17, v210, 48
	v_readlane_b32 s2, v210, 0
	v_readlane_b32 s3, v210, 32
	v_readlane_b32 s20, v211, 16
	v_readlane_b32 s21, v211, 48
	v_readlane_b32 s26, v211, 0
	v_readlane_b32 s27, v211, 32
	v_mov_b32_e32 v210, s2
	v_add_f32_e32 v210, s16, v210
	v_add_f32_e32 v210, s3, v210
	v_add_f32_e32 v210, s17, v210
	v_mov_b32_e32 v211, s26
	v_add_f32_e32 v211, s20, v211
	v_add_f32_e32 v211, s27, v211
	v_add_f32_e32 v211, s21, v211
	v_fmamk_f32 v204, v204, 0x3c800000, v190
	v_fmamk_f32 v205, v205, 0x3c800000, v190
	v_fmamk_f32 v206, v206, 0x3c800000, v190
	v_fmamk_f32 v207, v207, 0x3c800000, v190
	v_fmamk_f32 v208, v208, 0x3c800000, v190
	v_fmamk_f32 v209, v209, 0x3c800000, v190
	v_fmamk_f32 v210, v210, 0x3c800000, v190
	v_fmamk_f32 v211, v211, 0x3c800000, v190
	v_rsq_f32_e32 v204, v204
	v_rsq_f32_e32 v205, v205
	v_rsq_f32_e32 v206, v206
	v_rsq_f32_e32 v207, v207
	v_rsq_f32_e32 v208, v208
	v_rsq_f32_e32 v209, v209
	v_rsq_f32_e32 v210, v210
	v_rsq_f32_e32 v211, v211
	v_mul_f32_e32 v230, v230, v204
	v_mul_f32_e32 v231, v231, v205
	v_mul_f32_e32 v232, v232, v206
	v_mul_f32_e32 v233, v233, v207
	v_mul_f32_e32 v234, v234, v208
	v_mul_f32_e32 v235, v235, v209
	v_mul_f32_e32 v236, v236, v210
	v_mul_f32_e32 v237, v237, v211
	v_fma_f32 v230, v230, v65, v141
	v_fma_f32 v231, v231, v65, v141
	v_fma_f32 v232, v232, v65, v141
	v_fma_f32 v233, v233, v65, v141
	v_fma_f32 v234, v234, v65, v141
	v_fma_f32 v235, v235, v65, v141
	v_fma_f32 v236, v236, v65, v141
	v_fma_f32 v237, v237, v65, v141
	v_fmac_f32_e32 v230, v212, v238
	v_fmac_f32_e32 v231, v213, v239
	v_fmac_f32_e32 v232, v214, v240
	v_fmac_f32_e32 v233, v215, v241
	v_fmac_f32_e32 v234, v216, v242
	v_fmac_f32_e32 v235, v217, v243
	v_fmac_f32_e32 v236, v218, v244
	v_fmac_f32_e32 v237, v219, v245
	v_bfe_u32 v204, v230, 16, 1
	v_bfe_u32 v205, v231, 16, 1
	v_bfe_u32 v206, v232, 16, 1
	v_bfe_u32 v207, v233, 16, 1
	v_bfe_u32 v208, v234, 16, 1
	v_bfe_u32 v209, v235, 16, 1
	v_bfe_u32 v210, v236, 16, 1
	v_bfe_u32 v211, v237, 16, 1
	v_add3_u32 v230, v230, v204, s82
	v_add3_u32 v231, v231, v205, s82
	v_add3_u32 v232, v232, v206, s82
	v_add3_u32 v233, v233, v207, s82
	v_add3_u32 v234, v234, v208, s82
	v_add3_u32 v235, v235, v209, s82
	v_add3_u32 v236, v236, v210, s82
	v_add3_u32 v237, v237, v211, s82
	global_store_short_d16_hi v[226:227], v230, off
	v_lshl_add_u64 v[226:227], v[226:227], 0, v[228:229]
	global_store_short_d16_hi v[226:227], v231, off
	v_lshl_add_u64 v[226:227], v[226:227], 0, v[228:229]
	global_store_short_d16_hi v[226:227], v232, off
	v_lshl_add_u64 v[226:227], v[226:227], 0, v[228:229]
	global_store_short_d16_hi v[226:227], v233, off
	v_lshl_add_u64 v[226:227], v[226:227], 0, v[228:229]
	global_store_short_d16_hi v[226:227], v234, off
	v_lshl_add_u64 v[226:227], v[226:227], 0, v[228:229]
	global_store_short_d16_hi v[226:227], v235, off
	v_lshl_add_u64 v[226:227], v[226:227], 0, v[228:229]
	global_store_short_d16_hi v[226:227], v236, off
	v_lshl_add_u64 v[226:227], v[226:227], 0, v[228:229]
	global_store_short_d16_hi v[226:227], v237, off
	s_branch .LBB0_510
